# plus a static s_setprio 1 for waves 0-3 during the two Toeplitz MFMA streams only
# baseline (speedup 1.0000x reference)
.LBB0_456:
	s_or_b64 exec, exec, s[48:49]
	s_waitcnt vmcnt(1)
	v_lshlrev_b32_e32 v6, 16, v10
	v_and_b32_e32 v10, 0xffff0000, v10
	v_mov_b32_e32 v22, v10
	v_and_b32_e32 v47, 16, v12
	v_and_b32_e32 v46, 0xffff0000, v11
	v_lshlrev_b32_e32 v11, 16, v11
	s_waitcnt vmcnt(1)
	v_lshlrev_b32_e32 v23, 16, v23
	v_pk_mul_f32 v[22:23], v[30:31], v[22:23]
	v_mov_b32_e32 v24, v31
	v_mov_b32_e32 v25, v31
	v_mov_b32_e32 v32, v30
	v_mov_b32_e32 v33, v30
	s_waitcnt vmcnt(0)
	v_lshlrev_b32_e32 v7, 16, v7
	v_pk_fma_f32 v[22:23], v[30:31], v[6:7], v[22:23] op_sel:[0,0,1] op_sel_hi:[1,0,0]
	v_pk_mov_b32 v[30:31], v[10:11], v[46:47] op_sel:[1,0]
	v_mov_b32_e32 v29, v28
	v_and_b32_e32 v39, 0xffff0000, v13
	v_and_b32_e32 v41, 16, v13
	v_and_b32_e32 v40, 0xffff0000, v12
	v_lshlrev_b32_e32 v45, 16, v13
	v_lshlrev_b32_e32 v13, 16, v12
	v_mov_b32_e32 v12, v46
	v_pk_mul_f32 v[30:31], v[32:33], v[30:31]
	v_pk_fma_f32 v[22:23], v[28:29], v[10:11], v[22:23]
	v_pk_fma_f32 v[10:11], v[24:25], v[10:11], v[30:31]
	v_pk_mov_b32 v[30:31], v[12:13], v[40:41] op_sel:[1,0]
	v_mov_b32_e32 v38, v45
	v_pk_mul_f32 v[30:31], v[32:33], v[30:31]
	v_mov_b32_e32 v44, v40
	v_pk_fma_f32 v[10:11], v[28:29], v[12:13], v[10:11]
	v_pk_fma_f32 v[12:13], v[24:25], v[12:13], v[30:31]
	v_pk_mul_f32 v[30:31], v[32:33], v[38:39]
	v_mov_b32_e32 v8, v39
	v_pk_fma_f32 v[24:25], v[24:25], v[44:45], v[30:31]
	s_waitcnt vmcnt(0)
	v_lshlrev_b32_e32 v31, 16, v5
	v_mov_b32_e32 v36, v18
	v_mov_b32_e32 v37, v18
	v_pk_fma_f32 v[12:13], v[28:29], v[44:45], v[12:13]
	s_waitcnt vmcnt(1)
	v_lshlrev_b32_e32 v9, 16, v9
	v_pk_fma_f32 v[8:9], v[28:29], v[8:9], v[24:25]
	v_and_b32_e32 v25, 0xffff0000, v5
	v_and_b32_e32 v28, 0xffff0000, v4
	v_mov_b32_e32 v24, v31
	v_mov_b32_e32 v34, v19
	v_mov_b32_e32 v35, v19
	v_mov_b32_e32 v30, v28
	v_pk_mul_f32 v[32:33], v[36:37], v[24:25]
	v_mov_b32_e32 v17, v16
	v_pk_fma_f32 v[32:33], v[34:35], v[30:31], v[32:33]
	v_mov_b32_e32 v20, v25
	s_waitcnt vmcnt(0)
	v_lshlrev_b32_e32 v21, 16, v21
	v_pk_fma_f32 v[20:21], v[16:17], v[20:21], v[32:33]
	v_and_b32_e32 v32, 0xffff0000, v2
	v_mov_b32_e32 v27, v26
	v_and_b32_e32 v25, 16, v4
	v_and_b32_e32 v24, 0xffff0000, v3
	v_lshlrev_b32_e32 v33, 16, v3
	v_mov_b32_e32 v6, v32
	v_pk_add_f32 v[22:23], v[26:27], v[22:23]
	v_pk_add_f32 v[10:11], v[26:27], v[10:11]
	v_pk_add_f32 v[12:13], v[26:27], v[12:13]
	v_pk_add_f32 v[8:9], v[26:27], v[8:9]
	v_lshlrev_b32_e32 v26, 16, v2
	v_pk_mul_f32 v[2:3], v[18:19], v[6:7]
	v_pk_mov_b32 v[6:7], v[32:33], v[24:25] op_sel:[1,0]
	v_and_b32_e32 v29, 16, v5
	v_pk_mul_f32 v[6:7], v[36:37], v[6:7]
	v_lshlrev_b32_e32 v5, 16, v4
	v_mov_b32_e32 v4, v24
	v_pk_fma_f32 v[2:3], v[18:19], v[26:27], v[2:3] op_sel:[0,0,1] op_sel_hi:[1,0,0]
	v_pk_fma_f32 v[6:7], v[34:35], v[32:33], v[6:7]
	v_mov_b32_e32 v15, v14
	v_pk_fma_f32 v[2:3], v[16:17], v[32:33], v[2:3]
	v_pk_fma_f32 v[6:7], v[16:17], v[4:5], v[6:7]
	v_pk_add_f32 v[2:3], v[14:15], v[2:3]
	v_pk_add_f32 v[6:7], v[14:15], v[6:7]
	v_pk_mul_f32 v[2:3], v[22:23], v[2:3]
	v_pk_mul_f32 v[6:7], v[10:11], v[6:7]
	v_cvt_pk_bf16_f32 v2, v2, v3
	v_cvt_pk_bf16_f32 v3, v6, v7
	v_pk_mov_b32 v[6:7], v[4:5], v[28:29] op_sel:[1,0]
	v_pk_add_f32 v[20:21], v[14:15], v[20:21]
	v_pk_mul_f32 v[6:7], v[36:37], v[6:7]
	s_mov_b64 s[48:49], -1
	v_pk_fma_f32 v[4:5], v[34:35], v[4:5], v[6:7]
	v_pk_mul_f32 v[6:7], v[8:9], v[20:21]
	v_pk_fma_f32 v[4:5], v[16:17], v[30:31], v[4:5]
	s_nop 0
	v_pk_add_f32 v[4:5], v[14:15], v[4:5]
	s_nop 0
	v_pk_mul_f32 v[4:5], v[12:13], v[4:5]
	s_nop 0
	v_cvt_pk_bf16_f32 v4, v4, v5
	v_cvt_pk_bf16_f32 v5, v6, v7
	v_add_u32_e32 v6, s44, v43
	s_and_b64 s[44:45], s[30:31], exec
	v_add_u32_e32 v183, v6, v42
	s_cselect_b32 s44, 10, 14
	ds_write_b128 v183, v[2:5]
	v_lshlrev_b32_e32 v2, s44, v163
	v_add_u32_e32 v117, 0, v2
	v_mov_b32_e32 v2, s47
	v_mad_u32_u24 v182, s85, v163, v2
	v_sub_u32_e32 v2, s46, v111
	v_add_u32_e32 v184, v2, v120
	v_lshrrev_b32_e32 v2, s93, v164
	v_mul_u32_u24_e32 v2, s91, v2
	v_and_b32_e32 v3, s92, v111
	v_add3_u32 v180, v2, s90, v3
	v_lshlrev_b32_e32 v2, 1, v184
	v_add_u32_e32 v3, 0x7f, v180
	s_andn2_b64 vcc, exec, s[42:43]
	v_and_b32_e32 v185, 2, v2
	v_lshrrev_b32_e32 v187, 2, v3
	v_lshlrev_b32_e32 v186, 6, v3
	s_waitcnt lgkmcnt(0)
	s_barrier
	s_cbranch_vccnz .LBB0_472
	v_cmp_gt_u32_e32 vcc, 0x100, v1
	s_cbranch_vccz .Ltoep_prio_smp
	s_setprio 1

.Ltoep_seg6:
	s_waitcnt lgkmcnt(2)
	v_alignbyte_b32 v98, v195, v194, v185
	v_alignbyte_b32 v99, v196, v195, v185
	v_alignbyte_b32 v100, v197, v196, v185
	v_alignbyte_b32 v101, v198, v197, v185
	v_alignbyte_b32 v102, v201, v200, v185
	v_alignbyte_b32 v103, v202, v201, v185
	v_alignbyte_b32 v104, v203, v202, v185
	v_alignbyte_b32 v105, v204, v203, v185
	v_add_u32_e32 v206, -64, v206
	ds_read2_b32 v[194:195], v206 offset1:1
	ds_read2_b32 v[196:197], v206 offset0:2 offset1:3
	ds_read_b32 v198, v206 offset:16
	ds_read2_b32 v[200:201], v206 offset0:8 offset1:9
	ds_read2_b32 v[202:203], v206 offset0:10 offset1:11
	ds_read_b32 v204, v206 offset:48
	s_waitcnt lgkmcnt(7)
	v_mfma_f32_32x32x16_bf16 v[50:65], v[98:101], v[90:93], v[50:65]
	ds_read_b128 v[90:93], v207 offset:6144
	v_add_u32_e32 v209, -1, v209
	v_lshrrev_b32_e32 v210, 2, v209
	v_lshl_add_u32 v189, v209, 6, v182
	s_waitcnt lgkmcnt(7)
	v_mfma_f32_32x32x16_bf16 v[50:65], v[102:105], v[94:97], v[50:65]
	ds_read_b128 v[94:97], v208 offset:6144
	v_bitop3_b32 v211, v210, v113, 3 bitop3:0x6c
	v_bitop3_b32 v188, v210, v155, 3 bitop3:0x6c
	v_lshl_add_u32 v207, v211, 4, v189
	v_lshl_add_u32 v208, v188, 4, v189
	s_addk_i32 s42, 0x1
	s_cmpk_lt_i32 s42, 0x7f
	s_cbranch_scc1 .Ltoep_seg6
	s_waitcnt lgkmcnt(0)
	v_alignbyte_b32 v98, v195, v194, v185
	v_alignbyte_b32 v99, v196, v195, v185
	v_alignbyte_b32 v100, v197, v196, v185
	v_alignbyte_b32 v101, v198, v197, v185
	v_alignbyte_b32 v102, v201, v200, v185
	v_alignbyte_b32 v103, v202, v201, v185
	v_alignbyte_b32 v104, v203, v202, v185
	v_alignbyte_b32 v105, v204, v203, v185
	s_nop 1
	v_mfma_f32_32x32x16_bf16 v[50:65], v[98:101], v[90:93], v[50:65]
	v_mfma_f32_32x32x16_bf16 v[50:65], v[102:105], v[94:97], v[50:65]
	s_setprio 0
	s_mov_b64 s[48:49], 0
.LBB0_472:
	s_and_b64 vcc, exec, s[48:49]
	s_cbranch_vccz .LBB0_475
	v_cmp_gt_u32_e32 vcc, 0x100, v1
	s_cbranch_vccz .Ltoep_prio_pr
	s_setprio 1

.Ltoep_prompt:
	s_waitcnt lgkmcnt(8)
	v_alignbyte_b32 v98, v195, v194, v185
	v_alignbyte_b32 v99, v196, v195, v185
	v_alignbyte_b32 v100, v197, v196, v185
	v_alignbyte_b32 v101, v198, v197, v185
	v_alignbyte_b32 v102, v201, v200, v185
	v_alignbyte_b32 v103, v202, v201, v185
	v_alignbyte_b32 v104, v203, v202, v185
	v_alignbyte_b32 v105, v204, v203, v185
	v_add_u32_e32 v206, -64, v206
	ds_read2_b32 v[194:195], v206 offset1:1
	ds_read2_b32 v[196:197], v206 offset0:2 offset1:3
	ds_read_b32 v198, v206 offset:16
	ds_read2_b32 v[200:201], v206 offset0:8 offset1:9
	ds_read2_b32 v[202:203], v206 offset0:10 offset1:11
	ds_read_b32 v204, v206 offset:48
	v_lshrrev_b32_e32 v210, 2, v209
	v_lshl_add_u32 v189, v209, 6, v182
	v_bitop3_b32 v211, v210, v113, 3 bitop3:0x6c
	v_bitop3_b32 v188, v210, v155, 3 bitop3:0x6c
	v_lshl_add_u32 v199, v211, 4, v189
	v_lshl_add_u32 v205, v188, 4, v189
	s_waitcnt lgkmcnt(13)
	v_mfma_f32_32x32x16_bf16 v[2:17], v[98:101], v[66:69], v[2:17]
	ds_read_b128 v[66:69], v199
	s_waitcnt lgkmcnt(13)
	v_mfma_f32_32x32x16_bf16 v[2:17], v[102:105], v[70:73], v[2:17]
	ds_read_b128 v[70:73], v205
	v_add_u32_e32 v207, 60, v209
	v_lshrrev_b32_e32 v210, 2, v207
	v_lshl_add_u32 v189, v207, 6, v182
	v_bitop3_b32 v211, v210, v113, 3 bitop3:0x6c
	v_bitop3_b32 v188, v210, v155, 3 bitop3:0x6c
	v_lshl_add_u32 v199, v211, 4, v189
	v_lshl_add_u32 v205, v188, 4, v189
	s_waitcnt lgkmcnt(13)
	v_mfma_f32_32x32x16_bf16 v[18:33], v[98:101], v[74:77], v[18:33]
	ds_read_b128 v[74:77], v199
	s_waitcnt lgkmcnt(13)
	v_mfma_f32_32x32x16_bf16 v[18:33], v[102:105], v[78:81], v[18:33]
	ds_read_b128 v[78:81], v205
	v_add_u32_e32 v207, 120, v209
	v_lshrrev_b32_e32 v210, 2, v207
	v_lshl_add_u32 v189, v207, 6, v182
	v_bitop3_b32 v211, v210, v113, 3 bitop3:0x6c
	v_bitop3_b32 v188, v210, v155, 3 bitop3:0x6c
	v_lshl_add_u32 v199, v211, 4, v189
	v_lshl_add_u32 v205, v188, 4, v189
	s_waitcnt lgkmcnt(13)
	v_mfma_f32_32x32x16_bf16 v[34:49], v[98:101], v[82:85], v[34:49]
	ds_read_b128 v[82:85], v199
	s_waitcnt lgkmcnt(13)
	v_mfma_f32_32x32x16_bf16 v[34:49], v[102:105], v[86:89], v[34:49]
	ds_read_b128 v[86:89], v205
	v_add_u32_e32 v207, 180, v209
	v_lshrrev_b32_e32 v210, 2, v207
	v_lshl_add_u32 v189, v207, 6, v182
	v_bitop3_b32 v211, v210, v113, 3 bitop3:0x6c
	v_bitop3_b32 v188, v210, v155, 3 bitop3:0x6c
	v_lshl_add_u32 v199, v211, 4, v189
	v_lshl_add_u32 v205, v188, 4, v189
	s_waitcnt lgkmcnt(13)
	v_mfma_f32_32x32x16_bf16 v[50:65], v[98:101], v[90:93], v[50:65]
	ds_read_b128 v[90:93], v199
	s_waitcnt lgkmcnt(13)
	v_mfma_f32_32x32x16_bf16 v[50:65], v[102:105], v[94:97], v[50:65]
	ds_read_b128 v[94:97], v205
	v_add_u32_e32 v209, -1, v209
	s_add_i32 s42, s42, 1
	s_cmp_lt_i32 s42, 7
	s_cbranch_scc1 .Ltoep_prompt
	s_waitcnt lgkmcnt(0)
	v_alignbyte_b32 v98, v195, v194, v185
	v_alignbyte_b32 v99, v196, v195, v185
	v_alignbyte_b32 v100, v197, v196, v185
	v_alignbyte_b32 v101, v198, v197, v185
	v_alignbyte_b32 v102, v201, v200, v185
	v_alignbyte_b32 v103, v202, v201, v185
	v_alignbyte_b32 v104, v203, v202, v185
	v_alignbyte_b32 v105, v204, v203, v185
	s_nop 1
	v_mfma_f32_32x32x16_bf16 v[2:17], v[98:101], v[66:69], v[2:17]
	v_mfma_f32_32x32x16_bf16 v[2:17], v[102:105], v[70:73], v[2:17]
	v_mfma_f32_32x32x16_bf16 v[18:33], v[98:101], v[74:77], v[18:33]
	v_mfma_f32_32x32x16_bf16 v[18:33], v[102:105], v[78:81], v[18:33]
	v_mfma_f32_32x32x16_bf16 v[34:49], v[98:101], v[82:85], v[34:49]
	v_mfma_f32_32x32x16_bf16 v[34:49], v[102:105], v[86:89], v[34:49]
	v_mfma_f32_32x32x16_bf16 v[50:65], v[98:101], v[90:93], v[50:65]
	v_mfma_f32_32x32x16_bf16 v[50:65], v[102:105], v[94:97], v[50:65]
	s_setprio 0
